# GEMM K=2048 loops: back-edge rotated - loop-carried scalar updates and next-iteration address setup moved from after the loop-back barrier into the last MFMA block
# baseline (speedup 1.0000x reference)
; #define PG8_STAGE(bufoff, gbase, voff) do { _Pragma("unroll") for (int _i = 0; _i < 2; ++_i) \
;         __builtin_amdgcn_global_load_lds((const unsigned*)((const char*)(gbase) + (voff)[_i]), (PG8_LAS unsigned*)(lds + (bufoff) + ldsw + _i * 8192), 16, 0, 0); } while (0)
; #define PG8_LDA(dst, b, h) do { _Pragma("unroll") for (int m = 0; m < 4; ++m) _Pragma("unroll") for (int k = 0; k < 2; ++k) dst[m][k] = *(const PG8_LAS bf16x8*)(lds + PG8_SA(b, h) + aoff + m * 2048 + k * 1024); } while (0)
; #define PG8_LDB(dst, b, h) do { _Pragma("unroll") for (int n = 0; n < 2; ++n) _Pragma("unroll") for (int k = 0; k < 2; ++k) dst[n][k] = *(const PG8_LAS bf16x8*)(lds + PG8_SB(b, h) + boff + n * 2048 + k * 1024); } while (0)
; #define PG8_MMA(ai, bj, At, Bt) do { __builtin_amdgcn_s_setprio(1); _Pragma("unroll") for (int m = 0; m < 4; ++m) _Pragma("unroll") for (int n = 0; n < 2; ++n) _Pragma("unroll") for (int k = 0; k < 2; ++k) \
;         acc[ai][bj][m][n] = __builtin_amdgcn_mfma_f32_16x16x32_bf16(Bt[n][k], At[m][k], acc[ai][bj][m][n], 0, 0, 0); __builtin_amdgcn_s_setprio(0); } while (0)
; #define PG8_WAIT_V(n) asm volatile("s_waitcnt vmcnt(" #n ")" ::: "memory")
; #define PG8_WAIT_L(n) asm volatile("s_waitcnt lgkmcnt(" #n ")" ::: "memory")
; #define PG8_BAR __builtin_amdgcn_s_barrier()
; #define PG8_SCHED __builtin_amdgcn_sched_barrier(0)
; template <class Epi, class Sched, bool ALIGN_EPI = false, bool SP2 = false>
; __device__ __forceinline__ void gemm_phase(PG8_LAS unsigned char* lds, const Gemm g, const Sched& S, const Epi& E) {
;     ...
;             PG8_LDB(B0, 0, 0); PG8_LDB(B1, 0, 1); PG8_SCHED; PG8_LDA(At, 0, 0); PG8_STAGE(PG8_SA(1, 1), a1 + hstepB, voffA);
;             PG8_WAIT_V(8); PG8_WAIT_L(0); PG8_BAR; PG8_MMA(0, 0, At, B0); PG8_MMA(0, 1, At, B1); PG8_BAR; PG8_SCHED;
;             PG8_LDA(At, 0, 1); PG8_STAGE(PG8_SB(0, 0), b2, voffB); PG8_STAGE(PG8_SB(0, 1), b2 + hstepB, voffB); PG8_STAGE(PG8_SA(0, 0), a2, voffA);
.Lg232_body:
	v_add_u32_e32 v152, s31, v169
	v_add_u32_e32 v175, s60, v169
	ds_read_b128 v[128:131], v152
	ds_read_b128 v[132:135], v152 offset:1024
	ds_read_b128 v[148:151], v152 offset:2048
	ds_read_b128 v[152:155], v152 offset:3072
	ds_read_b128 v[156:159], v175
	ds_read_b128 v[160:163], v175 offset:1024
	ds_read_b128 v[164:167], v175 offset:2048
	ds_read_b128 v[176:179], v175 offset:3072
	v_lshl_add_u64 v[212:213], s[36:37], 0, v[144:145]
	s_add_i32 m0, s17, 0xc000
	ds_read_b128 v[180:183], v174
	ds_read_b128 v[184:187], v174 offset:1024
	ds_read_b128 v[188:191], v174 offset:2048
	ds_read_b128 v[192:195], v174 offset:3072
	ds_read_b128 v[196:199], v174 offset:4096
	ds_read_b128 v[200:203], v174 offset:5120
	ds_read_b128 v[204:207], v174 offset:6144
	ds_read_b128 v[208:211], v174 offset:7168
	global_load_lds_dwordx4 v[212:213], off
	v_lshl_add_u64 v[212:213], s[36:37], 0, v[146:147]
	s_add_i32 m0, s17, 0xe000
	s_nop 0
	global_load_lds_dwordx4 v[212:213], off
	s_waitcnt vmcnt(8)
	s_waitcnt lgkmcnt(0)
	s_barrier
	s_setprio 1
	s_waitcnt lgkmcnt(0)
	v_mfma_f32_16x16x32_bf16 v[124:127], v[128:131], v[180:183], v[124:127]
	v_mfma_f32_16x16x32_bf16 v[124:127], v[132:135], v[184:187], v[124:127]
	v_mfma_f32_16x16x32_bf16 v[120:123], v[148:151], v[180:183], v[120:123]
	v_mfma_f32_16x16x32_bf16 v[120:123], v[152:155], v[184:187], v[120:123]
	v_mfma_f32_16x16x32_bf16 v[108:111], v[128:131], v[188:191], v[108:111]
	v_mfma_f32_16x16x32_bf16 v[108:111], v[132:135], v[192:195], v[108:111]
	v_mfma_f32_16x16x32_bf16 v[104:107], v[148:151], v[188:191], v[104:107]
	v_mfma_f32_16x16x32_bf16 v[104:107], v[152:155], v[192:195], v[104:107]
	v_mfma_f32_16x16x32_bf16 v[92:95], v[128:131], v[196:199], v[92:95]
	v_mfma_f32_16x16x32_bf16 v[92:95], v[132:135], v[200:203], v[92:95]
	v_mfma_f32_16x16x32_bf16 v[88:91], v[148:151], v[196:199], v[88:91]
	v_mfma_f32_16x16x32_bf16 v[88:91], v[152:155], v[200:203], v[88:91]
	v_mfma_f32_16x16x32_bf16 v[76:79], v[128:131], v[204:207], v[76:79]
	v_mfma_f32_16x16x32_bf16 v[76:79], v[132:135], v[208:211], v[76:79]
	v_mfma_f32_16x16x32_bf16 v[72:75], v[148:151], v[204:207], v[72:75]
	v_mfma_f32_16x16x32_bf16 v[72:75], v[152:155], v[208:211], v[72:75]
	s_setprio 0
	s_setprio 1
	v_mfma_f32_16x16x32_bf16 v[116:119], v[156:159], v[180:183], v[116:119]
	v_mfma_f32_16x16x32_bf16 v[116:119], v[160:163], v[184:187], v[116:119]
	v_mfma_f32_16x16x32_bf16 v[112:115], v[164:167], v[180:183], v[112:115]
	v_mfma_f32_16x16x32_bf16 v[112:115], v[176:179], v[184:187], v[112:115]
	v_mfma_f32_16x16x32_bf16 v[100:103], v[156:159], v[188:191], v[100:103]
	v_mfma_f32_16x16x32_bf16 v[100:103], v[160:163], v[192:195], v[100:103]
	v_mfma_f32_16x16x32_bf16 v[96:99], v[164:167], v[188:191], v[96:99]
	v_mfma_f32_16x16x32_bf16 v[96:99], v[176:179], v[192:195], v[96:99]
	v_mfma_f32_16x16x32_bf16 v[84:87], v[156:159], v[196:199], v[84:87]
	v_mfma_f32_16x16x32_bf16 v[84:87], v[160:163], v[200:203], v[84:87]
	v_mfma_f32_16x16x32_bf16 v[80:83], v[164:167], v[196:199], v[80:83]
	v_mfma_f32_16x16x32_bf16 v[80:83], v[176:179], v[200:203], v[80:83]
	v_mfma_f32_16x16x32_bf16 v[68:71], v[156:159], v[204:207], v[68:71]
	v_mfma_f32_16x16x32_bf16 v[68:71], v[160:163], v[208:211], v[68:71]
	v_mfma_f32_16x16x32_bf16 v[64:67], v[164:167], v[204:207], v[64:67]
	v_mfma_f32_16x16x32_bf16 v[64:67], v[176:179], v[208:211], v[64:67]
	s_setprio 0
	s_barrier
	s_add_i32 s31, s31, s14
	v_lshl_add_u64 v[212:213], s[40:41], 0, v[220:221]
	s_mov_b32 m0, s31
	ds_read_b128 v[180:183], v174 offset:16384
	ds_read_b128 v[184:187], v174 offset:17408
	ds_read_b128 v[188:191], v174 offset:18432
	ds_read_b128 v[192:195], v174 offset:19456
	ds_read_b128 v[196:199], v174 offset:20480
	ds_read_b128 v[200:203], v174 offset:21504
	ds_read_b128 v[204:207], v174 offset:22528
	ds_read_b128 v[208:211], v174 offset:23552
	global_load_lds_dwordx4 v[212:213], off
	s_add_i32 m0, s31, 0x2000
	s_add_u32 s44, s40, 0x4000
	v_lshl_add_u64 v[212:213], s[40:41], 0, v[136:137]
	s_addc_u32 s45, s41, 0
	s_add_i32 s31, s60, s14
	global_load_lds_dwordx4 v[212:213], off
	v_lshl_add_u64 v[212:213], s[44:45], 0, v[220:221]
	s_mov_b32 m0, s31
	s_nop 0
	global_load_lds_dwordx4 v[212:213], off
	v_lshl_add_u64 v[212:213], s[44:45], 0, v[136:137]
	s_add_i32 m0, s31, 0x2000
	s_nop 0
	global_load_lds_dwordx4 v[212:213], off
	v_lshl_add_u64 v[212:213], s[42:43], 0, v[140:141]
	s_mov_b32 m0, s17
	s_nop 0
	global_load_lds_dwordx4 v[212:213], off
	v_lshl_add_u64 v[212:213], s[42:43], 0, v[138:139]
	s_mov_b32 m0, s18
	s_nop 0
	global_load_lds_dwordx4 v[212:213], off
	s_waitcnt vmcnt(8)
	s_waitcnt lgkmcnt(0)
	s_barrier
; #define PG8_STAGE(bufoff, gbase, voff) do { _Pragma("unroll") for (int _i = 0; _i < 2; ++_i) \
;         __builtin_amdgcn_global_load_lds((const unsigned*)((const char*)(gbase) + (voff)[_i]), (PG8_LAS unsigned*)(lds + (bufoff) + ldsw + _i * 8192), 16, 0, 0); } while (0)
; #define PG8_LDA(dst, b, h) do { _Pragma("unroll") for (int m = 0; m < 4; ++m) _Pragma("unroll") for (int k = 0; k < 2; ++k) dst[m][k] = *(const PG8_LAS bf16x8*)(lds + PG8_SA(b, h) + aoff + m * 2048 + k * 1024); } while (0)
; #define PG8_LDB(dst, b, h) do { _Pragma("unroll") for (int n = 0; n < 2; ++n) _Pragma("unroll") for (int k = 0; k < 2; ++k) dst[n][k] = *(const PG8_LAS bf16x8*)(lds + PG8_SB(b, h) + boff + n * 2048 + k * 1024); } while (0)
; #define PG8_MMA(ai, bj, At, Bt) do { __builtin_amdgcn_s_setprio(1); _Pragma("unroll") for (int m = 0; m < 4; ++m) _Pragma("unroll") for (int n = 0; n < 2; ++n) _Pragma("unroll") for (int k = 0; k < 2; ++k) \
;         acc[ai][bj][m][n] = __builtin_amdgcn_mfma_f32_16x16x32_bf16(Bt[n][k], At[m][k], acc[ai][bj][m][n], 0, 0, 0); __builtin_amdgcn_s_setprio(0); } while (0)
; #define PG8_WAIT_V(n) asm volatile("s_waitcnt vmcnt(" #n ")" ::: "memory")
; #define PG8_WAIT_L(n) asm volatile("s_waitcnt lgkmcnt(" #n ")" ::: "memory")
; #define PG8_BAR __builtin_amdgcn_s_barrier()
; #define PG8_SCHED __builtin_amdgcn_sched_barrier(0)
; template <class Epi, class Sched, bool ALIGN_EPI = false, bool SP2 = false>
; __device__ __forceinline__ void gemm_phase(PG8_LAS unsigned char* lds, const Gemm g, const Sched& S, const Epi& E) {
;     ...
;             PG8_WAIT_V(8); PG8_WAIT_L(0); PG8_BAR; PG8_MMA(1, 0, At, B0); PG8_MMA(1, 1, At, B1); PG8_BAR; PG8_SCHED;
;             PG8_LDB(B0, 1, 0); PG8_LDB(B1, 1, 1); PG8_SCHED; PG8_LDA(At, 1, 0); PG8_STAGE(PG8_SA(0, 1), a2 + hstepB, voffA);
;             PG8_WAIT_V(8); PG8_WAIT_L(0); PG8_BAR; PG8_MMA(0, 0, At, B0); PG8_MMA(0, 1, At, B1); PG8_BAR; PG8_SCHED;
	s_setprio 1
	s_waitcnt lgkmcnt(0)
	v_mfma_f32_16x16x32_bf16 v[60:63], v[128:131], v[180:183], v[60:63]
	v_mfma_f32_16x16x32_bf16 v[60:63], v[132:135], v[184:187], v[60:63]
	v_mfma_f32_16x16x32_bf16 v[56:59], v[148:151], v[180:183], v[56:59]
	v_mfma_f32_16x16x32_bf16 v[56:59], v[152:155], v[184:187], v[56:59]
	v_mfma_f32_16x16x32_bf16 v[48:51], v[128:131], v[188:191], v[48:51]
	v_mfma_f32_16x16x32_bf16 v[48:51], v[132:135], v[192:195], v[48:51]
	v_mfma_f32_16x16x32_bf16 v[40:43], v[148:151], v[188:191], v[40:43]
	v_mfma_f32_16x16x32_bf16 v[40:43], v[152:155], v[192:195], v[40:43]
	v_mfma_f32_16x16x32_bf16 v[32:35], v[128:131], v[196:199], v[32:35]
	v_mfma_f32_16x16x32_bf16 v[32:35], v[132:135], v[200:203], v[32:35]
	v_mfma_f32_16x16x32_bf16 v[24:27], v[148:151], v[196:199], v[24:27]
	v_mfma_f32_16x16x32_bf16 v[24:27], v[152:155], v[200:203], v[24:27]
	v_mfma_f32_16x16x32_bf16 v[16:19], v[128:131], v[204:207], v[16:19]
	v_mfma_f32_16x16x32_bf16 v[16:19], v[132:135], v[208:211], v[16:19]
	v_mfma_f32_16x16x32_bf16 v[8:11], v[148:151], v[204:207], v[8:11]
	v_mfma_f32_16x16x32_bf16 v[8:11], v[152:155], v[208:211], v[8:11]
	s_setprio 0
	s_setprio 1
	v_mfma_f32_16x16x32_bf16 v[52:55], v[156:159], v[180:183], v[52:55]
	v_mfma_f32_16x16x32_bf16 v[52:55], v[160:163], v[184:187], v[52:55]
	v_mfma_f32_16x16x32_bf16 v[44:47], v[164:167], v[180:183], v[44:47]
	v_mfma_f32_16x16x32_bf16 v[44:47], v[176:179], v[184:187], v[44:47]
	v_mfma_f32_16x16x32_bf16 v[36:39], v[156:159], v[188:191], v[36:39]
	v_mfma_f32_16x16x32_bf16 v[36:39], v[160:163], v[192:195], v[36:39]
	v_mfma_f32_16x16x32_bf16 v[28:31], v[164:167], v[188:191], v[28:31]
	v_mfma_f32_16x16x32_bf16 v[28:31], v[176:179], v[192:195], v[28:31]
	v_mfma_f32_16x16x32_bf16 v[20:23], v[156:159], v[196:199], v[20:23]
	v_mfma_f32_16x16x32_bf16 v[20:23], v[160:163], v[200:203], v[20:23]
	v_mfma_f32_16x16x32_bf16 v[12:15], v[164:167], v[196:199], v[12:15]
	v_mfma_f32_16x16x32_bf16 v[12:15], v[176:179], v[200:203], v[12:15]
	v_mfma_f32_16x16x32_bf16 v[4:7], v[156:159], v[204:207], v[4:7]
	v_mfma_f32_16x16x32_bf16 v[4:7], v[160:163], v[208:211], v[4:7]
	v_mfma_f32_16x16x32_bf16 v[0:3], v[164:167], v[204:207], v[0:3]
	v_mfma_f32_16x16x32_bf16 v[0:3], v[176:179], v[208:211], v[0:3]
	s_setprio 0
	s_barrier
	s_add_i32 s31, 0, 0x18000
	s_add_i32 s44, 0, 0x1c000
	v_add_u32_e32 v152, s31, v169
	v_add_u32_e32 v175, s44, v169
	ds_read_b128 v[128:131], v152
	ds_read_b128 v[132:135], v152 offset:1024
	ds_read_b128 v[148:151], v152 offset:2048
	ds_read_b128 v[152:155], v152 offset:3072
	ds_read_b128 v[156:159], v175
	ds_read_b128 v[160:163], v175 offset:1024
	ds_read_b128 v[164:167], v175 offset:2048
	ds_read_b128 v[176:179], v175 offset:3072
	s_add_u32 s42, s42, 0x4000
	s_addc_u32 s43, s43, 0
	s_mov_b32 m0, s19
	v_lshl_add_u64 v[212:213], s[42:43], 0, v[140:141]
	ds_read_b128 v[180:183], v174 offset:32768
	ds_read_b128 v[184:187], v174 offset:33792
	ds_read_b128 v[188:191], v174 offset:34816
	ds_read_b128 v[192:195], v174 offset:35840
	ds_read_b128 v[196:199], v174 offset:36864
	ds_read_b128 v[200:203], v174 offset:37888
	ds_read_b128 v[204:207], v174 offset:38912
	ds_read_b128 v[208:211], v174 offset:39936
	global_load_lds_dwordx4 v[212:213], off
	v_lshl_add_u64 v[212:213], s[42:43], 0, v[138:139]
	s_mov_b32 m0, s20
	s_nop 0
	global_load_lds_dwordx4 v[212:213], off
	s_waitcnt vmcnt(8)
	s_waitcnt lgkmcnt(0)
	s_barrier
	s_setprio 1
	s_waitcnt lgkmcnt(0)
	v_mfma_f32_16x16x32_bf16 v[124:127], v[128:131], v[180:183], v[124:127]
	v_mfma_f32_16x16x32_bf16 v[124:127], v[132:135], v[184:187], v[124:127]
	v_mfma_f32_16x16x32_bf16 v[120:123], v[148:151], v[180:183], v[120:123]
	v_mfma_f32_16x16x32_bf16 v[120:123], v[152:155], v[184:187], v[120:123]
	v_mfma_f32_16x16x32_bf16 v[108:111], v[128:131], v[188:191], v[108:111]
	v_mfma_f32_16x16x32_bf16 v[108:111], v[132:135], v[192:195], v[108:111]
	v_mfma_f32_16x16x32_bf16 v[104:107], v[148:151], v[188:191], v[104:107]
	v_mfma_f32_16x16x32_bf16 v[104:107], v[152:155], v[192:195], v[104:107]
	v_mfma_f32_16x16x32_bf16 v[92:95], v[128:131], v[196:199], v[92:95]
	v_mfma_f32_16x16x32_bf16 v[92:95], v[132:135], v[200:203], v[92:95]
	v_mfma_f32_16x16x32_bf16 v[88:91], v[148:151], v[196:199], v[88:91]
	v_mfma_f32_16x16x32_bf16 v[88:91], v[152:155], v[200:203], v[88:91]
	v_mfma_f32_16x16x32_bf16 v[76:79], v[128:131], v[204:207], v[76:79]
	v_mfma_f32_16x16x32_bf16 v[76:79], v[132:135], v[208:211], v[76:79]
	v_mfma_f32_16x16x32_bf16 v[72:75], v[148:151], v[204:207], v[72:75]
	v_mfma_f32_16x16x32_bf16 v[72:75], v[152:155], v[208:211], v[72:75]
	s_setprio 0
	s_setprio 1
	v_mfma_f32_16x16x32_bf16 v[116:119], v[156:159], v[180:183], v[116:119]
	v_mfma_f32_16x16x32_bf16 v[116:119], v[160:163], v[184:187], v[116:119]
	v_mfma_f32_16x16x32_bf16 v[112:115], v[164:167], v[180:183], v[112:115]
	v_mfma_f32_16x16x32_bf16 v[112:115], v[176:179], v[184:187], v[112:115]
	v_mfma_f32_16x16x32_bf16 v[100:103], v[156:159], v[188:191], v[100:103]
	v_mfma_f32_16x16x32_bf16 v[100:103], v[160:163], v[192:195], v[100:103]
	v_mfma_f32_16x16x32_bf16 v[96:99], v[164:167], v[188:191], v[96:99]
	v_mfma_f32_16x16x32_bf16 v[96:99], v[176:179], v[192:195], v[96:99]
	v_mfma_f32_16x16x32_bf16 v[84:87], v[156:159], v[196:199], v[84:87]
	v_mfma_f32_16x16x32_bf16 v[84:87], v[160:163], v[200:203], v[84:87]
	v_mfma_f32_16x16x32_bf16 v[80:83], v[164:167], v[196:199], v[80:83]
	v_mfma_f32_16x16x32_bf16 v[80:83], v[176:179], v[200:203], v[80:83]
	v_mfma_f32_16x16x32_bf16 v[68:71], v[156:159], v[204:207], v[68:71]
	v_mfma_f32_16x16x32_bf16 v[68:71], v[160:163], v[208:211], v[68:71]
	v_mfma_f32_16x16x32_bf16 v[64:67], v[164:167], v[204:207], v[64:67]
	v_mfma_f32_16x16x32_bf16 v[64:67], v[176:179], v[208:211], v[64:67]
	s_setprio 0
	s_barrier
; #define PG8_STAGE(bufoff, gbase, voff) do { _Pragma("unroll") for (int _i = 0; _i < 2; ++_i) \
;         __builtin_amdgcn_global_load_lds((const unsigned*)((const char*)(gbase) + (voff)[_i]), (PG8_LAS unsigned*)(lds + (bufoff) + ldsw + _i * 8192), 16, 0, 0); } while (0)
; #define PG8_LDA(dst, b, h) do { _Pragma("unroll") for (int m = 0; m < 4; ++m) _Pragma("unroll") for (int k = 0; k < 2; ++k) dst[m][k] = *(const PG8_LAS bf16x8*)(lds + PG8_SA(b, h) + aoff + m * 2048 + k * 1024); } while (0)
; #define PG8_MMA(ai, bj, At, Bt) do { __builtin_amdgcn_s_setprio(1); _Pragma("unroll") for (int m = 0; m < 4; ++m) _Pragma("unroll") for (int n = 0; n < 2; ++n) _Pragma("unroll") for (int k = 0; k < 2; ++k) \
;         acc[ai][bj][m][n] = __builtin_amdgcn_mfma_f32_16x16x32_bf16(Bt[n][k], At[m][k], acc[ai][bj][m][n], 0, 0, 0); __builtin_amdgcn_s_setprio(0); } while (0)
; #define PG8_WAIT_V(n) asm volatile("s_waitcnt vmcnt(" #n ")" ::: "memory")
; #define PG8_WAIT_L(n) asm volatile("s_waitcnt lgkmcnt(" #n ")" ::: "memory")
; #define PG8_BAR __builtin_amdgcn_s_barrier()
; #define PG8_SCHED __builtin_amdgcn_sched_barrier(0)
; template <class Epi, class Sched, bool ALIGN_EPI = false, bool SP2 = false>
; __device__ __forceinline__ void gemm_phase(PG8_LAS unsigned char* lds, const Gemm g, const Sched& S, const Epi& E) {
;     ...
;         for (int t = 0; t < nt; t += 2) {
;             const bool last = (t == nt - 2);
;             const char* a1 = cA + (size_t)(t + 1) * kstepB;
;             const char* a2 = last ? nA : cA + (size_t)(t + 2) * kstepB; const char* b2 = last ? nB : cB + (size_t)(t + 2) * kstepB;
;             const char* a3 = a2 + kstepB; const char* b3 = b2 + kstepB;
;             if (last && has_next) S.a_ready(nxt);
;     ...
;             PG8_LDA(At, 1, 1); PG8_STAGE(PG8_SB(1, 0), b3, voffB); PG8_STAGE(PG8_SB(1, 1), b3 + hstepB, voffB); PG8_STAGE(PG8_SA(1, 0), a3, voffA);
;             PG8_WAIT_V(8); PG8_WAIT_L(0); PG8_BAR; PG8_MMA(1, 0, At, B0); PG8_MMA(1, 1, At, B1); PG8_BAR; PG8_SCHED;
	s_add_u32 s42, s40, 0x8000
	s_addc_u32 s43, s41, 0
	s_add_i32 s31, s31, s14
	v_lshl_add_u64 v[212:213], s[42:43], 0, v[220:221]
	s_mov_b32 m0, s31
	ds_read_b128 v[180:183], v174 offset:49152
	ds_read_b128 v[184:187], v174 offset:50176
	ds_read_b128 v[188:191], v174 offset:51200
	ds_read_b128 v[192:195], v174 offset:52224
	ds_read_b128 v[196:199], v174 offset:53248
	ds_read_b128 v[200:203], v174 offset:54272
	ds_read_b128 v[204:207], v174 offset:55296
	ds_read_b128 v[208:211], v174 offset:56320
	global_load_lds_dwordx4 v[212:213], off
	s_add_i32 m0, s31, 0x2000
	s_add_u32 s40, s40, 0xc000
	v_lshl_add_u64 v[212:213], s[42:43], 0, v[136:137]
	s_addc_u32 s41, s41, 0
	s_add_i32 s31, s44, s14
	global_load_lds_dwordx4 v[212:213], off
	v_lshl_add_u64 v[212:213], s[40:41], 0, v[220:221]
	s_mov_b32 m0, s31
	s_nop 0
	global_load_lds_dwordx4 v[212:213], off
	v_lshl_add_u64 v[212:213], s[40:41], 0, v[136:137]
	s_add_i32 m0, s31, 0x2000
	s_nop 0
	global_load_lds_dwordx4 v[212:213], off
	v_lshl_add_u64 v[212:213], s[38:39], 0, v[140:141]
	s_mov_b32 m0, s21
	s_nop 0
	global_load_lds_dwordx4 v[212:213], off
	v_lshl_add_u64 v[212:213], s[38:39], 0, v[138:139]
	s_mov_b32 m0, s22
	s_nop 0
	global_load_lds_dwordx4 v[212:213], off
	s_waitcnt vmcnt(8)
	s_waitcnt lgkmcnt(0)
	s_barrier
	s_setprio 1
	s_waitcnt lgkmcnt(0)
	v_mfma_f32_16x16x32_bf16 v[60:63], v[128:131], v[180:183], v[60:63]
	v_mfma_f32_16x16x32_bf16 v[60:63], v[132:135], v[184:187], v[60:63]
	v_mfma_f32_16x16x32_bf16 v[56:59], v[148:151], v[180:183], v[56:59]
	v_mfma_f32_16x16x32_bf16 v[56:59], v[152:155], v[184:187], v[56:59]
	v_mfma_f32_16x16x32_bf16 v[48:51], v[128:131], v[188:191], v[48:51]
	v_mfma_f32_16x16x32_bf16 v[48:51], v[132:135], v[192:195], v[48:51]
	v_mfma_f32_16x16x32_bf16 v[40:43], v[148:151], v[188:191], v[40:43]
	v_mfma_f32_16x16x32_bf16 v[40:43], v[152:155], v[192:195], v[40:43]
	v_mfma_f32_16x16x32_bf16 v[32:35], v[128:131], v[196:199], v[32:35]
	v_mfma_f32_16x16x32_bf16 v[32:35], v[132:135], v[200:203], v[32:35]
	v_mfma_f32_16x16x32_bf16 v[24:27], v[148:151], v[196:199], v[24:27]
	v_mfma_f32_16x16x32_bf16 v[24:27], v[152:155], v[200:203], v[24:27]
	v_mfma_f32_16x16x32_bf16 v[16:19], v[128:131], v[204:207], v[16:19]
	v_mfma_f32_16x16x32_bf16 v[16:19], v[132:135], v[208:211], v[16:19]
	v_mfma_f32_16x16x32_bf16 v[8:11], v[148:151], v[204:207], v[8:11]
	v_mfma_f32_16x16x32_bf16 v[8:11], v[152:155], v[208:211], v[8:11]
	s_setprio 0
	s_setprio 1
	s_add_i32 s30, s30, 2
	s_add_u32 s36, s36, 0x10000
	s_addc_u32 s37, s37, 0
	s_add_u32 s28, s28, 0x10000
	s_addc_u32 s29, s29, 0
	s_cmp_gt_u32 s30, 29
	s_cbranch_scc1 .Lg232_skiph
	s_add_u32 s31, s36, 0x4000
	s_addc_u32 s38, s37, 0
	s_cmp_eq_u32 s30, 28
	s_cselect_b32 s42, s26, s31
	s_cselect_b32 s43, s13, s38
	s_cselect_b32 s40, s27, s28
	s_cselect_b32 s41, s11, s29
	s_add_u32 s38, s42, 0x8000
	s_addc_u32 s39, s43, 0
	s_add_i32 s31, 0, 0x10000
	s_add_i32 s60, 0, 0x14000
.Lg232_skiph:
	v_mfma_f32_16x16x32_bf16 v[52:55], v[156:159], v[180:183], v[52:55]
	v_mfma_f32_16x16x32_bf16 v[52:55], v[160:163], v[184:187], v[52:55]
	v_mfma_f32_16x16x32_bf16 v[44:47], v[164:167], v[180:183], v[44:47]
	v_mfma_f32_16x16x32_bf16 v[44:47], v[176:179], v[184:187], v[44:47]
	v_mfma_f32_16x16x32_bf16 v[36:39], v[156:159], v[188:191], v[36:39]
	v_mfma_f32_16x16x32_bf16 v[36:39], v[160:163], v[192:195], v[36:39]
	v_mfma_f32_16x16x32_bf16 v[28:31], v[164:167], v[188:191], v[28:31]
	v_mfma_f32_16x16x32_bf16 v[28:31], v[176:179], v[192:195], v[28:31]
	v_mfma_f32_16x16x32_bf16 v[20:23], v[156:159], v[196:199], v[20:23]
	v_mfma_f32_16x16x32_bf16 v[20:23], v[160:163], v[200:203], v[20:23]
	v_mfma_f32_16x16x32_bf16 v[12:15], v[164:167], v[196:199], v[12:15]
	v_mfma_f32_16x16x32_bf16 v[12:15], v[176:179], v[200:203], v[12:15]
	v_mfma_f32_16x16x32_bf16 v[4:7], v[156:159], v[204:207], v[4:7]
	v_mfma_f32_16x16x32_bf16 v[4:7], v[160:163], v[208:211], v[4:7]
	v_mfma_f32_16x16x32_bf16 v[0:3], v[164:167], v[204:207], v[0:3]
	v_mfma_f32_16x16x32_bf16 v[0:3], v[176:179], v[208:211], v[0:3]
	s_setprio 0
	s_barrier
	s_cmp_gt_u32 s30, 29
	s_cbranch_scc0 .Lg232_body
	s_and_b64 vcc, exec, s[8:9]
	s_cbranch_vccz .LBB0_235
	s_barrier

; #define PG8_STAGE(bufoff, gbase, voff) do { _Pragma("unroll") for (int _i = 0; _i < 2; ++_i) \
;         __builtin_amdgcn_global_load_lds((const unsigned*)((const char*)(gbase) + (voff)[_i]), (PG8_LAS unsigned*)(lds + (bufoff) + ldsw + _i * 8192), 16, 0, 0); } while (0)
; #define PG8_LDA(dst, b, h) do { _Pragma("unroll") for (int m = 0; m < 4; ++m) _Pragma("unroll") for (int k = 0; k < 2; ++k) dst[m][k] = *(const PG8_LAS bf16x8*)(lds + PG8_SA(b, h) + aoff + m * 2048 + k * 1024); } while (0)
; #define PG8_LDB(dst, b, h) do { _Pragma("unroll") for (int n = 0; n < 2; ++n) _Pragma("unroll") for (int k = 0; k < 2; ++k) dst[n][k] = *(const PG8_LAS bf16x8*)(lds + PG8_SB(b, h) + boff + n * 2048 + k * 1024); } while (0)
; #define PG8_MMA(ai, bj, At, Bt) do { __builtin_amdgcn_s_setprio(1); _Pragma("unroll") for (int m = 0; m < 4; ++m) _Pragma("unroll") for (int n = 0; n < 2; ++n) _Pragma("unroll") for (int k = 0; k < 2; ++k) \
;         acc[ai][bj][m][n] = __builtin_amdgcn_mfma_f32_16x16x32_bf16(Bt[n][k], At[m][k], acc[ai][bj][m][n], 0, 0, 0); __builtin_amdgcn_s_setprio(0); } while (0)
; #define PG8_WAIT_V(n) asm volatile("s_waitcnt vmcnt(" #n ")" ::: "memory")
; #define PG8_WAIT_L(n) asm volatile("s_waitcnt lgkmcnt(" #n ")" ::: "memory")
; #define PG8_BAR __builtin_amdgcn_s_barrier()
; #define PG8_SCHED __builtin_amdgcn_sched_barrier(0)
; template <class Epi, class Sched, bool ALIGN_EPI = false, bool SP2 = false>
; __device__ __forceinline__ void gemm_phase(PG8_LAS unsigned char* lds, const Gemm g, const Sched& S, const Epi& E) {
;     ...
;         for (int t = 0; t < nt; t += 2) {
;             const bool last = (t == nt - 2);
;             const char* a1 = cA + (size_t)(t + 1) * kstepB;
;             const char* a2 = last ? nA : cA + (size_t)(t + 2) * kstepB; const char* b2 = last ? nB : cB + (size_t)(t + 2) * kstepB;
;             const char* a3 = a2 + kstepB; const char* b3 = b2 + kstepB;
;             if (last && has_next) S.a_ready(nxt);
;             if constexpr (SP2) {
;             PG8_LDB(B0, 0, 0); PG8_LDB(B1, 0, 1); PG8_SCHED; PG8_LDA(At, 0, 0); PG8_STAGE(PG8_SA(1, 1), a1 + hstepB, voffA);
;             PG8_WAIT_V(8); PG8_WAIT_L(0); PG8_BAR; PG8_MMA(0, 0, At, B0); PG8_MMA(0, 1, At, B1); PG8_BAR; PG8_SCHED;
;             PG8_LDA(At, 0, 1); PG8_STAGE(PG8_SB(0, 0), b2, voffB); PG8_STAGE(PG8_SB(0, 1), b2 + hstepB, voffB); PG8_STAGE(PG8_SA(0, 0), a2, voffA);
.LBB0_263:
	s_add_u32 s38, s36, 0x4000
	s_addc_u32 s39, s37, 0
	s_cmp_eq_u32 s62, 28
	s_cselect_b32 s42, s30, s38
	s_cselect_b32 s43, s13, s39
	s_cselect_b32 s40, s31, s44
	s_cselect_b32 s41, s11, s45
	s_add_u32 s38, s42, 0x8000
	s_addc_u32 s39, s43, 0
	s_add_i32 s63, 0, 0x10000
	s_add_i32 s75, 0, 0x14000
.Lg263_body:
	v_add_u32_e32 v151, s63, v165
	ds_read_b128 v[128:131], v151
	ds_read_b128 v[132:135], v151 offset:1024
	ds_read_b128 v[152:155], v151 offset:2048
	ds_read_b128 v[156:159], v151 offset:3072
	v_add_u32_e32 v151, s75, v165
	ds_read_b128 v[160:163], v151
	ds_read_b128 v[170:173], v151 offset:1024
	ds_read_b128 v[174:177], v151 offset:2048
	ds_read_b128 v[178:181], v151 offset:3072
	v_lshl_add_u64 v[214:215], s[36:37], 0, v[146:147]
	s_add_i32 m0, s19, 0xc000
	ds_read_b128 v[182:185], v168
	ds_read_b128 v[186:189], v168 offset:1024
	ds_read_b128 v[190:193], v168 offset:2048
	ds_read_b128 v[194:197], v168 offset:3072
	ds_read_b128 v[198:201], v168 offset:4096
	ds_read_b128 v[202:205], v168 offset:5120
	ds_read_b128 v[206:209], v168 offset:6144
	ds_read_b128 v[210:213], v168 offset:7168
	global_load_lds_dwordx4 v[214:215], off
	v_lshl_add_u64 v[214:215], s[36:37], 0, v[148:149]
	s_add_i32 m0, s19, 0xe000
	s_nop 0
	global_load_lds_dwordx4 v[214:215], off
	s_waitcnt vmcnt(8)
	s_waitcnt lgkmcnt(0)
	s_barrier
	s_setprio 1
	s_waitcnt lgkmcnt(0)
	v_mfma_f32_16x16x32_bf16 v[124:127], v[128:131], v[182:185], v[124:127]
	v_mfma_f32_16x16x32_bf16 v[124:127], v[132:135], v[186:189], v[124:127]
	v_mfma_f32_16x16x32_bf16 v[116:119], v[152:155], v[182:185], v[116:119]
	v_mfma_f32_16x16x32_bf16 v[116:119], v[156:159], v[186:189], v[116:119]
	v_mfma_f32_16x16x32_bf16 v[108:111], v[128:131], v[190:193], v[108:111]
	v_mfma_f32_16x16x32_bf16 v[108:111], v[132:135], v[194:197], v[108:111]
	v_mfma_f32_16x16x32_bf16 v[100:103], v[152:155], v[190:193], v[100:103]
	v_mfma_f32_16x16x32_bf16 v[100:103], v[156:159], v[194:197], v[100:103]
	v_mfma_f32_16x16x32_bf16 v[92:95], v[128:131], v[198:201], v[92:95]
	v_mfma_f32_16x16x32_bf16 v[92:95], v[132:135], v[202:205], v[92:95]
	v_mfma_f32_16x16x32_bf16 v[84:87], v[152:155], v[198:201], v[84:87]
	v_mfma_f32_16x16x32_bf16 v[84:87], v[156:159], v[202:205], v[84:87]
	v_mfma_f32_16x16x32_bf16 v[76:79], v[128:131], v[206:209], v[76:79]
	v_mfma_f32_16x16x32_bf16 v[76:79], v[132:135], v[210:213], v[76:79]
	v_mfma_f32_16x16x32_bf16 v[68:71], v[152:155], v[206:209], v[68:71]
	v_mfma_f32_16x16x32_bf16 v[68:71], v[156:159], v[210:213], v[68:71]
	s_setprio 0
	s_setprio 1
	v_mfma_f32_16x16x32_bf16 v[120:123], v[160:163], v[182:185], v[120:123]
	v_mfma_f32_16x16x32_bf16 v[120:123], v[170:173], v[186:189], v[120:123]
	v_mfma_f32_16x16x32_bf16 v[112:115], v[174:177], v[182:185], v[112:115]
	v_mfma_f32_16x16x32_bf16 v[112:115], v[178:181], v[186:189], v[112:115]
	v_mfma_f32_16x16x32_bf16 v[104:107], v[160:163], v[190:193], v[104:107]
	v_mfma_f32_16x16x32_bf16 v[104:107], v[170:173], v[194:197], v[104:107]
	v_mfma_f32_16x16x32_bf16 v[96:99], v[174:177], v[190:193], v[96:99]
	v_mfma_f32_16x16x32_bf16 v[96:99], v[178:181], v[194:197], v[96:99]
	v_mfma_f32_16x16x32_bf16 v[88:91], v[160:163], v[198:201], v[88:91]
	v_mfma_f32_16x16x32_bf16 v[88:91], v[170:173], v[202:205], v[88:91]
	v_mfma_f32_16x16x32_bf16 v[80:83], v[174:177], v[198:201], v[80:83]
	v_mfma_f32_16x16x32_bf16 v[80:83], v[178:181], v[202:205], v[80:83]
	v_mfma_f32_16x16x32_bf16 v[72:75], v[160:163], v[206:209], v[72:75]
	v_mfma_f32_16x16x32_bf16 v[72:75], v[170:173], v[210:213], v[72:75]
	v_mfma_f32_16x16x32_bf16 v[64:67], v[174:177], v[206:209], v[64:67]
	v_mfma_f32_16x16x32_bf16 v[64:67], v[178:181], v[210:213], v[64:67]
	s_setprio 0
	s_barrier
	s_add_i32 s63, s63, s16
	v_lshl_add_u64 v[214:215], s[40:41], 0, v[140:141]
	s_mov_b32 m0, s63
	ds_read_b128 v[182:185], v168 offset:16384
	ds_read_b128 v[186:189], v168 offset:17408
	ds_read_b128 v[190:193], v168 offset:18432
	ds_read_b128 v[194:197], v168 offset:19456
	ds_read_b128 v[198:201], v168 offset:20480
	ds_read_b128 v[202:205], v168 offset:21504
	ds_read_b128 v[206:209], v168 offset:22528
	ds_read_b128 v[210:213], v168 offset:23552
	global_load_lds_dwordx4 v[214:215], off
	s_add_i32 m0, s63, 0x2000
	s_add_u32 s66, s40, 0x4000
	v_lshl_add_u64 v[214:215], s[40:41], 0, v[136:137]
	s_addc_u32 s67, s41, 0
	s_add_i32 s63, s75, s16
	global_load_lds_dwordx4 v[214:215], off
	v_lshl_add_u64 v[214:215], s[66:67], 0, v[140:141]
	s_mov_b32 m0, s63
	s_nop 0
	global_load_lds_dwordx4 v[214:215], off
	v_lshl_add_u64 v[214:215], s[66:67], 0, v[136:137]
	s_add_i32 m0, s63, 0x2000
	s_nop 0
	global_load_lds_dwordx4 v[214:215], off
	v_lshl_add_u64 v[214:215], s[42:43], 0, v[142:143]
	s_mov_b32 m0, s19
	s_nop 0
	global_load_lds_dwordx4 v[214:215], off
	v_lshl_add_u64 v[214:215], s[42:43], 0, v[138:139]
	s_mov_b32 m0, s20
	s_nop 0
	global_load_lds_dwordx4 v[214:215], off
	s_waitcnt vmcnt(8)
	s_waitcnt lgkmcnt(0)
	s_barrier
; #define PG8_STAGE(bufoff, gbase, voff) do { _Pragma("unroll") for (int _i = 0; _i < 2; ++_i) \
;         __builtin_amdgcn_global_load_lds((const unsigned*)((const char*)(gbase) + (voff)[_i]), (PG8_LAS unsigned*)(lds + (bufoff) + ldsw + _i * 8192), 16, 0, 0); } while (0)
; #define PG8_LDA(dst, b, h) do { _Pragma("unroll") for (int m = 0; m < 4; ++m) _Pragma("unroll") for (int k = 0; k < 2; ++k) dst[m][k] = *(const PG8_LAS bf16x8*)(lds + PG8_SA(b, h) + aoff + m * 2048 + k * 1024); } while (0)
; #define PG8_LDB(dst, b, h) do { _Pragma("unroll") for (int n = 0; n < 2; ++n) _Pragma("unroll") for (int k = 0; k < 2; ++k) dst[n][k] = *(const PG8_LAS bf16x8*)(lds + PG8_SB(b, h) + boff + n * 2048 + k * 1024); } while (0)
; #define PG8_MMA(ai, bj, At, Bt) do { __builtin_amdgcn_s_setprio(1); _Pragma("unroll") for (int m = 0; m < 4; ++m) _Pragma("unroll") for (int n = 0; n < 2; ++n) _Pragma("unroll") for (int k = 0; k < 2; ++k) \
;         acc[ai][bj][m][n] = __builtin_amdgcn_mfma_f32_16x16x32_bf16(Bt[n][k], At[m][k], acc[ai][bj][m][n], 0, 0, 0); __builtin_amdgcn_s_setprio(0); } while (0)
; #define PG8_WAIT_V(n) asm volatile("s_waitcnt vmcnt(" #n ")" ::: "memory")
; #define PG8_WAIT_L(n) asm volatile("s_waitcnt lgkmcnt(" #n ")" ::: "memory")
; #define PG8_BAR __builtin_amdgcn_s_barrier()
; #define PG8_SCHED __builtin_amdgcn_sched_barrier(0)
; template <class Epi, class Sched, bool ALIGN_EPI = false, bool SP2 = false>
; __device__ __forceinline__ void gemm_phase(PG8_LAS unsigned char* lds, const Gemm g, const Sched& S, const Epi& E) {
;     ...
;             PG8_WAIT_V(8); PG8_WAIT_L(0); PG8_BAR; PG8_MMA(1, 0, At, B0); PG8_MMA(1, 1, At, B1); PG8_BAR; PG8_SCHED;
;             PG8_LDB(B0, 1, 0); PG8_LDB(B1, 1, 1); PG8_SCHED; PG8_LDA(At, 1, 0); PG8_STAGE(PG8_SA(0, 1), a2 + hstepB, voffA);
;             PG8_WAIT_V(8); PG8_WAIT_L(0); PG8_BAR; PG8_MMA(0, 0, At, B0); PG8_MMA(0, 1, At, B1); PG8_BAR; PG8_SCHED;
	s_setprio 1
	s_waitcnt lgkmcnt(0)
	v_mfma_f32_16x16x32_bf16 v[60:63], v[128:131], v[182:185], v[60:63]
	v_mfma_f32_16x16x32_bf16 v[60:63], v[132:135], v[186:189], v[60:63]
	v_mfma_f32_16x16x32_bf16 v[52:55], v[152:155], v[182:185], v[52:55]
	v_mfma_f32_16x16x32_bf16 v[52:55], v[156:159], v[186:189], v[52:55]
	v_mfma_f32_16x16x32_bf16 v[44:47], v[128:131], v[190:193], v[44:47]
	v_mfma_f32_16x16x32_bf16 v[44:47], v[132:135], v[194:197], v[44:47]
	v_mfma_f32_16x16x32_bf16 v[36:39], v[152:155], v[190:193], v[36:39]
	v_mfma_f32_16x16x32_bf16 v[36:39], v[156:159], v[194:197], v[36:39]
	v_mfma_f32_16x16x32_bf16 v[28:31], v[128:131], v[198:201], v[28:31]
	v_mfma_f32_16x16x32_bf16 v[28:31], v[132:135], v[202:205], v[28:31]
	v_mfma_f32_16x16x32_bf16 v[20:23], v[152:155], v[198:201], v[20:23]
	v_mfma_f32_16x16x32_bf16 v[20:23], v[156:159], v[202:205], v[20:23]
	v_mfma_f32_16x16x32_bf16 v[12:15], v[128:131], v[206:209], v[12:15]
	v_mfma_f32_16x16x32_bf16 v[12:15], v[132:135], v[210:213], v[12:15]
	v_mfma_f32_16x16x32_bf16 v[4:7], v[152:155], v[206:209], v[4:7]
	v_mfma_f32_16x16x32_bf16 v[4:7], v[156:159], v[210:213], v[4:7]
	s_setprio 0
	s_setprio 1
	v_mfma_f32_16x16x32_bf16 v[56:59], v[160:163], v[182:185], v[56:59]
	v_mfma_f32_16x16x32_bf16 v[56:59], v[170:173], v[186:189], v[56:59]
	v_mfma_f32_16x16x32_bf16 v[48:51], v[174:177], v[182:185], v[48:51]
	v_mfma_f32_16x16x32_bf16 v[48:51], v[178:181], v[186:189], v[48:51]
	v_mfma_f32_16x16x32_bf16 v[40:43], v[160:163], v[190:193], v[40:43]
	v_mfma_f32_16x16x32_bf16 v[40:43], v[170:173], v[194:197], v[40:43]
	v_mfma_f32_16x16x32_bf16 v[32:35], v[174:177], v[190:193], v[32:35]
	v_mfma_f32_16x16x32_bf16 v[32:35], v[178:181], v[194:197], v[32:35]
	v_mfma_f32_16x16x32_bf16 v[24:27], v[160:163], v[198:201], v[24:27]
	v_mfma_f32_16x16x32_bf16 v[24:27], v[170:173], v[202:205], v[24:27]
	v_mfma_f32_16x16x32_bf16 v[16:19], v[174:177], v[198:201], v[16:19]
	v_mfma_f32_16x16x32_bf16 v[16:19], v[178:181], v[202:205], v[16:19]
	v_mfma_f32_16x16x32_bf16 v[8:11], v[160:163], v[206:209], v[8:11]
	v_mfma_f32_16x16x32_bf16 v[8:11], v[170:173], v[210:213], v[8:11]
	v_mfma_f32_16x16x32_bf16 v[0:3], v[174:177], v[206:209], v[0:3]
	v_mfma_f32_16x16x32_bf16 v[0:3], v[178:181], v[210:213], v[0:3]
	s_setprio 0
	s_barrier
	s_add_i32 s63, 0, 0x18000
	v_add_u32_e32 v151, s63, v165
	s_add_i32 s66, 0, 0x1c000
	ds_read_b128 v[128:131], v151
	ds_read_b128 v[132:135], v151 offset:1024
	ds_read_b128 v[152:155], v151 offset:2048
	ds_read_b128 v[156:159], v151 offset:3072
	v_add_u32_e32 v151, s66, v165
	ds_read_b128 v[160:163], v151
	ds_read_b128 v[170:173], v151 offset:1024
	ds_read_b128 v[174:177], v151 offset:2048
	ds_read_b128 v[178:181], v151 offset:3072
	s_add_u32 s42, s42, 0x4000
	s_addc_u32 s43, s43, 0
	s_mov_b32 m0, s21
	v_lshl_add_u64 v[214:215], s[42:43], 0, v[142:143]
	ds_read_b128 v[182:185], v168 offset:32768
	ds_read_b128 v[186:189], v168 offset:33792
	ds_read_b128 v[190:193], v168 offset:34816
	ds_read_b128 v[194:197], v168 offset:35840
	ds_read_b128 v[198:201], v168 offset:36864
	ds_read_b128 v[202:205], v168 offset:37888
	ds_read_b128 v[206:209], v168 offset:38912
	ds_read_b128 v[210:213], v168 offset:39936
	global_load_lds_dwordx4 v[214:215], off
	v_lshl_add_u64 v[214:215], s[42:43], 0, v[138:139]
	s_mov_b32 m0, s22
	s_nop 0
	global_load_lds_dwordx4 v[214:215], off
	s_waitcnt vmcnt(8)
	s_waitcnt lgkmcnt(0)
	s_barrier
	s_setprio 1
	s_waitcnt lgkmcnt(0)
	v_mfma_f32_16x16x32_bf16 v[124:127], v[128:131], v[182:185], v[124:127]
	v_mfma_f32_16x16x32_bf16 v[124:127], v[132:135], v[186:189], v[124:127]
	v_mfma_f32_16x16x32_bf16 v[116:119], v[152:155], v[182:185], v[116:119]
	v_mfma_f32_16x16x32_bf16 v[116:119], v[156:159], v[186:189], v[116:119]
	v_mfma_f32_16x16x32_bf16 v[108:111], v[128:131], v[190:193], v[108:111]
	v_mfma_f32_16x16x32_bf16 v[108:111], v[132:135], v[194:197], v[108:111]
	v_mfma_f32_16x16x32_bf16 v[100:103], v[152:155], v[190:193], v[100:103]
	v_mfma_f32_16x16x32_bf16 v[100:103], v[156:159], v[194:197], v[100:103]
	v_mfma_f32_16x16x32_bf16 v[92:95], v[128:131], v[198:201], v[92:95]
	v_mfma_f32_16x16x32_bf16 v[92:95], v[132:135], v[202:205], v[92:95]
	v_mfma_f32_16x16x32_bf16 v[84:87], v[152:155], v[198:201], v[84:87]
	v_mfma_f32_16x16x32_bf16 v[84:87], v[156:159], v[202:205], v[84:87]
	v_mfma_f32_16x16x32_bf16 v[76:79], v[128:131], v[206:209], v[76:79]
	v_mfma_f32_16x16x32_bf16 v[76:79], v[132:135], v[210:213], v[76:79]
	v_mfma_f32_16x16x32_bf16 v[68:71], v[152:155], v[206:209], v[68:71]
	v_mfma_f32_16x16x32_bf16 v[68:71], v[156:159], v[210:213], v[68:71]
	s_setprio 0
	s_setprio 1
	v_mfma_f32_16x16x32_bf16 v[120:123], v[160:163], v[182:185], v[120:123]
	v_mfma_f32_16x16x32_bf16 v[120:123], v[170:173], v[186:189], v[120:123]
	v_mfma_f32_16x16x32_bf16 v[112:115], v[174:177], v[182:185], v[112:115]
	v_mfma_f32_16x16x32_bf16 v[112:115], v[178:181], v[186:189], v[112:115]
	v_mfma_f32_16x16x32_bf16 v[104:107], v[160:163], v[190:193], v[104:107]
	v_mfma_f32_16x16x32_bf16 v[104:107], v[170:173], v[194:197], v[104:107]
	v_mfma_f32_16x16x32_bf16 v[96:99], v[174:177], v[190:193], v[96:99]
	v_mfma_f32_16x16x32_bf16 v[96:99], v[178:181], v[194:197], v[96:99]
	v_mfma_f32_16x16x32_bf16 v[88:91], v[160:163], v[198:201], v[88:91]
	v_mfma_f32_16x16x32_bf16 v[88:91], v[170:173], v[202:205], v[88:91]
	v_mfma_f32_16x16x32_bf16 v[80:83], v[174:177], v[198:201], v[80:83]
	v_mfma_f32_16x16x32_bf16 v[80:83], v[178:181], v[202:205], v[80:83]
	v_mfma_f32_16x16x32_bf16 v[72:75], v[160:163], v[206:209], v[72:75]
	v_mfma_f32_16x16x32_bf16 v[72:75], v[170:173], v[210:213], v[72:75]
	v_mfma_f32_16x16x32_bf16 v[64:67], v[174:177], v[206:209], v[64:67]
	v_mfma_f32_16x16x32_bf16 v[64:67], v[178:181], v[210:213], v[64:67]
	s_setprio 0
	s_barrier
; #define PG8_STAGE(bufoff, gbase, voff) do { _Pragma("unroll") for (int _i = 0; _i < 2; ++_i) \
;         __builtin_amdgcn_global_load_lds((const unsigned*)((const char*)(gbase) + (voff)[_i]), (PG8_LAS unsigned*)(lds + (bufoff) + ldsw + _i * 8192), 16, 0, 0); } while (0)
; #define PG8_LDA(dst, b, h) do { _Pragma("unroll") for (int m = 0; m < 4; ++m) _Pragma("unroll") for (int k = 0; k < 2; ++k) dst[m][k] = *(const PG8_LAS bf16x8*)(lds + PG8_SA(b, h) + aoff + m * 2048 + k * 1024); } while (0)
; #define PG8_MMA(ai, bj, At, Bt) do { __builtin_amdgcn_s_setprio(1); _Pragma("unroll") for (int m = 0; m < 4; ++m) _Pragma("unroll") for (int n = 0; n < 2; ++n) _Pragma("unroll") for (int k = 0; k < 2; ++k) \
;         acc[ai][bj][m][n] = __builtin_amdgcn_mfma_f32_16x16x32_bf16(Bt[n][k], At[m][k], acc[ai][bj][m][n], 0, 0, 0); __builtin_amdgcn_s_setprio(0); } while (0)
; #define PG8_WAIT_V(n) asm volatile("s_waitcnt vmcnt(" #n ")" ::: "memory")
; #define PG8_WAIT_L(n) asm volatile("s_waitcnt lgkmcnt(" #n ")" ::: "memory")
; #define PG8_BAR __builtin_amdgcn_s_barrier()
; #define PG8_SCHED __builtin_amdgcn_sched_barrier(0)
; template <class Epi, class Sched, bool ALIGN_EPI = false, bool SP2 = false>
; __device__ __forceinline__ void gemm_phase(PG8_LAS unsigned char* lds, const Gemm g, const Sched& S, const Epi& E) {
;     ...
;         for (int t = 0; t < nt; t += 2) {
;             const bool last = (t == nt - 2);
;             const char* a1 = cA + (size_t)(t + 1) * kstepB;
;             const char* a2 = last ? nA : cA + (size_t)(t + 2) * kstepB; const char* b2 = last ? nB : cB + (size_t)(t + 2) * kstepB;
;             const char* a3 = a2 + kstepB; const char* b3 = b2 + kstepB;
;             if (last && has_next) S.a_ready(nxt);
;     ...
;             PG8_LDA(At, 1, 1); PG8_STAGE(PG8_SB(1, 0), b3, voffB); PG8_STAGE(PG8_SB(1, 1), b3 + hstepB, voffB); PG8_STAGE(PG8_SA(1, 0), a3, voffA);
;             PG8_WAIT_V(8); PG8_WAIT_L(0); PG8_BAR; PG8_MMA(1, 0, At, B0); PG8_MMA(1, 1, At, B1); PG8_BAR; PG8_SCHED;
	s_add_u32 s42, s40, 0x8000
	s_addc_u32 s43, s41, 0
	s_add_i32 s63, s63, s16
	v_lshl_add_u64 v[214:215], s[42:43], 0, v[140:141]
	s_mov_b32 m0, s63
	ds_read_b128 v[182:185], v168 offset:49152
	ds_read_b128 v[186:189], v168 offset:50176
	ds_read_b128 v[190:193], v168 offset:51200
	ds_read_b128 v[194:197], v168 offset:52224
	ds_read_b128 v[198:201], v168 offset:53248
	ds_read_b128 v[202:205], v168 offset:54272
	ds_read_b128 v[206:209], v168 offset:55296
	ds_read_b128 v[210:213], v168 offset:56320
	global_load_lds_dwordx4 v[214:215], off
	s_add_i32 m0, s63, 0x2000
	s_add_u32 s40, s40, 0xc000
	v_lshl_add_u64 v[214:215], s[42:43], 0, v[136:137]
	s_addc_u32 s41, s41, 0
	s_add_i32 s42, s66, s16
	global_load_lds_dwordx4 v[214:215], off
	v_lshl_add_u64 v[214:215], s[40:41], 0, v[140:141]
	s_mov_b32 m0, s42
	s_nop 0
	global_load_lds_dwordx4 v[214:215], off
	v_lshl_add_u64 v[214:215], s[40:41], 0, v[136:137]
	s_add_i32 m0, s42, 0x2000
	s_nop 0
	global_load_lds_dwordx4 v[214:215], off
	v_lshl_add_u64 v[214:215], s[38:39], 0, v[142:143]
	s_mov_b32 m0, s25
	s_nop 0
	global_load_lds_dwordx4 v[214:215], off
	v_lshl_add_u64 v[214:215], s[38:39], 0, v[138:139]
	s_mov_b32 m0, s26
	s_nop 0
	global_load_lds_dwordx4 v[214:215], off
	s_waitcnt vmcnt(8)
	s_waitcnt lgkmcnt(0)
	s_barrier
	s_setprio 1
	s_waitcnt lgkmcnt(0)
	v_mfma_f32_16x16x32_bf16 v[60:63], v[128:131], v[182:185], v[60:63]
	v_mfma_f32_16x16x32_bf16 v[60:63], v[132:135], v[186:189], v[60:63]
	v_mfma_f32_16x16x32_bf16 v[52:55], v[152:155], v[182:185], v[52:55]
	v_mfma_f32_16x16x32_bf16 v[52:55], v[156:159], v[186:189], v[52:55]
	v_mfma_f32_16x16x32_bf16 v[44:47], v[128:131], v[190:193], v[44:47]
	v_mfma_f32_16x16x32_bf16 v[44:47], v[132:135], v[194:197], v[44:47]
	v_mfma_f32_16x16x32_bf16 v[36:39], v[152:155], v[190:193], v[36:39]
	v_mfma_f32_16x16x32_bf16 v[36:39], v[156:159], v[194:197], v[36:39]
	v_mfma_f32_16x16x32_bf16 v[28:31], v[128:131], v[198:201], v[28:31]
	v_mfma_f32_16x16x32_bf16 v[28:31], v[132:135], v[202:205], v[28:31]
	v_mfma_f32_16x16x32_bf16 v[20:23], v[152:155], v[198:201], v[20:23]
	v_mfma_f32_16x16x32_bf16 v[20:23], v[156:159], v[202:205], v[20:23]
	v_mfma_f32_16x16x32_bf16 v[12:15], v[128:131], v[206:209], v[12:15]
	v_mfma_f32_16x16x32_bf16 v[12:15], v[132:135], v[210:213], v[12:15]
	v_mfma_f32_16x16x32_bf16 v[4:7], v[152:155], v[206:209], v[4:7]
	v_mfma_f32_16x16x32_bf16 v[4:7], v[156:159], v[210:213], v[4:7]
	s_setprio 0
	s_setprio 1
	s_add_i32 s62, s62, 2
	s_add_u32 s36, s36, 0x10000
	s_addc_u32 s37, s37, 0
	s_add_u32 s44, s44, 0x10000
	s_addc_u32 s45, s45, 0
	s_cmp_gt_u32 s62, 29
	s_cbranch_scc1 .Lg263_skiph
	s_add_u32 s38, s36, 0x4000
	s_addc_u32 s39, s37, 0
	s_cmp_eq_u32 s62, 28
	s_cselect_b32 s42, s30, s38
	s_cselect_b32 s43, s13, s39
	s_cselect_b32 s40, s31, s44
	s_cselect_b32 s41, s11, s45
	s_add_u32 s38, s42, 0x8000
	s_addc_u32 s39, s43, 0
	s_add_i32 s63, 0, 0x10000
	s_add_i32 s75, 0, 0x14000
.Lg263_skiph:
	v_mfma_f32_16x16x32_bf16 v[56:59], v[160:163], v[182:185], v[56:59]
	v_mfma_f32_16x16x32_bf16 v[56:59], v[170:173], v[186:189], v[56:59]
	v_mfma_f32_16x16x32_bf16 v[48:51], v[174:177], v[182:185], v[48:51]
	v_mfma_f32_16x16x32_bf16 v[48:51], v[178:181], v[186:189], v[48:51]
	v_mfma_f32_16x16x32_bf16 v[40:43], v[160:163], v[190:193], v[40:43]
	v_mfma_f32_16x16x32_bf16 v[40:43], v[170:173], v[194:197], v[40:43]
	v_mfma_f32_16x16x32_bf16 v[32:35], v[174:177], v[190:193], v[32:35]
	v_mfma_f32_16x16x32_bf16 v[32:35], v[178:181], v[194:197], v[32:35]
	v_mfma_f32_16x16x32_bf16 v[24:27], v[160:163], v[198:201], v[24:27]
	v_mfma_f32_16x16x32_bf16 v[24:27], v[170:173], v[202:205], v[24:27]
	v_mfma_f32_16x16x32_bf16 v[16:19], v[174:177], v[198:201], v[16:19]
	v_mfma_f32_16x16x32_bf16 v[16:19], v[178:181], v[202:205], v[16:19]
	v_mfma_f32_16x16x32_bf16 v[8:11], v[160:163], v[206:209], v[8:11]
	v_mfma_f32_16x16x32_bf16 v[8:11], v[170:173], v[210:213], v[8:11]
	v_mfma_f32_16x16x32_bf16 v[0:3], v[174:177], v[206:209], v[0:3]
	v_mfma_f32_16x16x32_bf16 v[0:3], v[178:181], v[210:213], v[0:3]
	s_setprio 0
	s_barrier
	s_cmp_gt_u32 s62, 29
	s_cbranch_scc0 .Lg263_body
	s_and_b64 vcc, exec, s[8:9]
	s_cbranch_vccz .LBB0_266
	s_barrier
